# DIFF attention: waves 4-7 run each half-step's K/V staging block after their P.V instead of before it (the SIMD's two waves offset by that block)
# speedup vs baseline: 1.0021x; 1.0021x over previous
; __device__ __forceinline__ void finishSM(f32x16& p0, f32x16& p1, float alpha, float& l_reg, bf16x8& pa0, bf16x8& pa1, bf16x8& pa2, bf16x8& pa3) {
; #pragma unroll
;   for (int r = 0; r < 16; ++r) p1[r] = __builtin_amdgcn_exp2f(p1[r]);
;   float ps = 0;
; #pragma unroll
;   for (int r = 0; r < 16; ++r) ps += p0[r];
; #pragma unroll
;   for (int r = 0; r < 16; ++r) ps += p1[r];
;   { auto rr = __builtin_amdgcn_permlane32_swap(__float_as_uint(ps), __float_as_uint(ps), false, false);
;     ps = __uint_as_float(rr[0]) + __uint_as_float(rr[1]); }
;   l_reg = l_reg * alpha + ps;
;     ...
;   PK4(p0, 0, pa0); PK4(p0, 8, pa1); PK4(p1, 0, pa2); PK4(p1, 8, pa3);
;     ...
; }
; template <int DQK, int KW, int QSP> __device__ __forceinline__ void qkt(f32x16& p0, f32x16& p1, const char* Ks, const int (&kb)[4], const bf16x8* qr, const char* qsp, const f32x16& cinit) {
;   p0 = cinit; p1 = cinit;
;   constexpr int N = DQK / 16;
;     ...
;   bf16x8 f0[2], f1[2];
;   f0[0] = KRD(0, 1); f1[0] = KRD(0, 0);
; #pragma unroll
;   for (int d0 = 0; d0 < N; ++d0) {
;     if (d0 + 1 < N) { f0[(d0 + 1) & 1] = KRD(d0 + 1, 1); f1[(d0 + 1) & 1] = KRD(d0 + 1, 0); }
;     __builtin_amdgcn_sched_barrier(0x406);
;     bf16x8 qf;
;     if constexpr (QSP > 0) { if (d0 >= N - QSP) qf = *reinterpret_cast<const bf16x8*>(qsp + (d0 - (N - QSP)) * 1024); else qf = qr[d0]; } else qf = qr[d0];
;     p0 = __builtin_amdgcn_mfma_f32_32x32x16_bf16(f0[d0 & 1], qf, p0, 0, 0, 0);
;     p1 = __builtin_amdgcn_mfma_f32_32x32x16_bf16(f1[d0 & 1], qf, p1, 0, 0, 0);
;     __builtin_amdgcn_sched_barrier(0x406); }
; template <int DQK, int KW, bool DIFF, int SDEPTH, int QSP, int NBUF>
; __device__ __forceinline__ void attn_unit(const UnitP& P, char* lds) {
;     ...
;   f32x16 pA0, pA1, pB0, pB1; float mnA, mnB, alA, alB; bf16x8 pa0, pa1, pa2, pa3; const int NT = P.nt;
;   if constexpr (NBUF == 3) {
.LBB0_316:
	s_lshl_b32 s10, s35, 14
	s_add_i32 s8, s10, 0
	v_add_u32_e32 v102, s8, v183
	ds_read_b128 v[98:101], v102 offset:49152
	v_add_u32_e32 v103, s8, v197
	ds_read_b128 v[200:203], v102 offset:57344
	ds_read_b128 v[222:225], v103 offset:49152
	ds_read_b128 v[226:229], v103 offset:57344
	v_add_u32_e32 v204, s8, v196
	v_exp_f32_e32 v205, v85
	v_exp_f32_e32 v97, v97
	s_waitcnt lgkmcnt(3)
	v_mfma_f32_32x32x16_bf16 v[114:129], v[98:101], v[142:145], v[66:81]
	s_waitcnt lgkmcnt(2)
	v_mfma_f32_32x32x16_bf16 v[98:113], v[200:203], v[142:145], v[66:81]
	ds_read_b128 v[200:203], v204 offset:49152
	ds_read_b128 v[230:233], v204 offset:57344
	v_add_u32_e32 v204, s8, v198
	s_waitcnt lgkmcnt(3)
	v_mfma_f32_32x32x16_bf16 v[114:129], v[222:225], v[138:141], v[114:129]
	s_waitcnt lgkmcnt(2)
	v_mfma_f32_32x32x16_bf16 v[98:113], v[226:229], v[138:141], v[98:113]
	ds_read_b128 v[222:225], v204 offset:49152
	ds_read_b128 v[226:229], v204 offset:57344
	v_exp_f32_e32 v204, v84
	s_waitcnt lgkmcnt(3)
	v_mfma_f32_32x32x16_bf16 v[114:129], v[200:203], v[134:137], v[114:129]
	v_exp_f32_e32 v202, v82
	v_add_f32_e32 v82, 0, v219
	v_add_f32_e32 v82, v221, v82
	v_add_f32_e32 v82, v217, v82
	v_add_f32_e32 v82, v220, v82
	v_add_f32_e32 v82, v215, v82
	v_add_f32_e32 v82, v218, v82
	v_add_f32_e32 v82, v214, v82
	v_add_f32_e32 v82, v216, v82
	v_add_f32_e32 v82, v211, v82
	v_add_f32_e32 v82, v213, v82
	v_add_f32_e32 v82, v209, v82
	v_add_f32_e32 v82, v212, v82
	s_waitcnt lgkmcnt(2)
	v_mfma_f32_32x32x16_bf16 v[98:113], v[230:233], v[134:137], v[98:113]
	v_add_f32_e32 v82, v207, v82
	v_exp_f32_e32 v203, v83
	v_add_f32_e32 v82, v210, v82
	v_add_f32_e32 v82, v206, v82
	v_add_f32_e32 v82, v208, v82
	v_add_f32_e32 v82, v202, v82
	v_add_f32_e32 v82, v203, v82
	s_waitcnt lgkmcnt(1)
	v_mfma_f32_32x32x16_bf16 v[114:129], v[222:225], v[130:133], v[114:129]
	v_exp_f32_e32 v222, v86
	v_exp_f32_e32 v223, v87
	v_exp_f32_e32 v224, v88
	v_add_f32_e32 v82, v204, v82
	v_exp_f32_e32 v225, v89
	v_add_f32_e32 v82, v205, v82
	v_add_f32_e32 v82, v222, v82
	s_waitcnt lgkmcnt(0)
	v_mfma_f32_32x32x16_bf16 v[98:113], v[226:229], v[130:133], v[98:113]
	v_exp_f32_e32 v226, v90
	v_exp_f32_e32 v227, v91
	v_add_f32_e32 v82, v223, v82
	v_exp_f32_e32 v228, v92
	v_add_f32_e32 v82, v224, v82
	v_exp_f32_e32 v229, v93
	v_add_f32_e32 v82, v225, v82
	v_exp_f32_e32 v230, v94
	v_add_f32_e32 v82, v226, v82
	v_exp_f32_e32 v231, v95
	v_add_f32_e32 v82, v227, v82
	v_exp_f32_e32 v232, v96
	v_add_f32_e32 v82, v228, v82
	v_add_f32_e32 v82, v229, v82
	v_add_f32_e32 v82, v230, v82
	v_add_f32_e32 v82, v231, v82
	v_add_f32_e32 v82, v232, v82
	v_add_f32_e32 v200, v97, v82
	v_mov_b32_e32 v201, v200
	v_cvt_pk_bf16_f32 v82, v219, v221
	v_cvt_pk_bf16_f32 v83, v217, v220
	v_cvt_pk_bf16_f32 v84, v215, v218
	s_nop 1
	v_permlane32_swap_b32_e32 v200, v201
	v_cvt_pk_bf16_f32 v85, v214, v216
	v_permlane32_swap_b32_e32 v82, v84
	v_cvt_pk_bf16_f32 v86, v211, v213
	v_cvt_pk_bf16_f32 v87, v209, v212
	v_cvt_pk_bf16_f32 v88, v207, v210
	v_cvt_pk_bf16_f32 v89, v206, v208
	v_cvt_pk_bf16_f32 v90, v202, v203
	v_cvt_pk_bf16_f32 v91, v204, v205
	v_cvt_pk_bf16_f32 v92, v222, v223
	v_cvt_pk_bf16_f32 v93, v224, v225
	v_cvt_pk_bf16_f32 v94, v226, v227
	v_cvt_pk_bf16_f32 v95, v228, v229
	v_cvt_pk_bf16_f32 v96, v230, v231
	v_cvt_pk_bf16_f32 v97, v232, v97
	v_permlane32_swap_b32_e32 v83, v85
	v_permlane32_swap_b32_e32 v86, v88
	v_permlane32_swap_b32_e32 v87, v89
	v_permlane32_swap_b32_e32 v90, v92
	v_permlane32_swap_b32_e32 v91, v93
	v_permlane32_swap_b32_e32 v94, v96
	v_permlane32_swap_b32_e32 v95, v97
	v_readlane_b32 s18, v255, 8
	s_nop 3
	s_cmp_ge_u32 s18, 4
	s_cbranch_scc1 .Ldw_skipA1
	s_lshl_b32 s13, s12, 14
	s_add_i32 s11, s13, 0
	v_add_u32_e32 v202, s11, v192
	s_waitcnt vmcnt(0)
	s_waitcnt vmcnt(3)
	ds_write_b128 v202, v[146:149]
	v_add_u32_e32 v146, s11, v193
	s_waitcnt vmcnt(1)
	ds_write_b128 v146, v[150:153]
	v_add_u32_e32 v146, s11, v194
	s_mov_b32 s8, 0xfffa0000
	s_waitcnt vmcnt(1)
	ds_write_b128 v146, v[154:157] offset:49152
	s_waitcnt vmcnt(0)
	ds_write_b128 v146, v[158:161] offset:57344
	v_add_co_u32_e32 v146, vcc, s8, v166
	s_mov_b32 s8, 0xfffc0000
	s_nop 0
	v_addc_co_u32_e32 v147, vcc, -1, v167, vcc
	v_add_co_u32_e32 v150, vcc, s8, v166
	s_mov_b32 s8, 0xfb7a0000
	s_nop 0
	v_addc_co_u32_e32 v151, vcc, -1, v167, vcc
	v_add_co_u32_e32 v154, vcc, s8, v166
	s_mov_b32 s8, 0xfb7c0000
	s_nop 0
	v_addc_co_u32_e32 v155, vcc, -1, v167, vcc
	v_add_co_u32_e32 v158, vcc, s8, v166
	global_load_dwordx4 v[146:149], v[146:147], off
	s_nop 0
	global_load_dwordx4 v[150:153], v[150:151], off
	v_addc_co_u32_e32 v159, vcc, -1, v167, vcc
	global_load_dwordx4 v[154:157], v[154:155], off
	s_nop 0
	global_load_dwordx4 v[158:161], v[158:159], off
; #define SBAR() __builtin_amdgcn_sched_barrier(0)
; template <bool FIRST> __device__ __forceinline__ void partialSM_ps(f32x16& p0, f32x16& p1, float& m_reg, float& alpha, f32x16& negm) {
;   float pmax = p0[0];
; #pragma unroll
;   for (int r = 1; r < 16; ++r) pmax = fmaxf(pmax, p0[r]);
; #pragma unroll
;   for (int r = 0; r < 16; ++r) pmax = fmaxf(pmax, p1[r]);
;   { auto rr = __builtin_amdgcn_permlane32_swap(__float_as_uint(pmax), __float_as_uint(pmax), false, false);
;     pmax = fmaxf(__uint_as_float(rr[0]), __uint_as_float(rr[1])); }
;   alpha = 1.f;
;   if (FIRST || !__builtin_expect(__all(pmax <= THRL), 1)) {
; template <int OFF> __device__ __forceinline__ s16x4 tr_read(int vb) {
;   s16x4 r; asm volatile("ds_read_b64_tr_b16 %0, %1 offset:%2" : "=&v"(r) : "v"(vb), "i"(OFF) : "memory"); return r;
; }
; template <int D0> __device__ __forceinline__ void pv_one(f32x16& od, int vb, bf16x8 pa0, bf16x8 pa1, bf16x8 pa2, bf16x8 pa3) {
;   const s16x4 l0 = tr_read<v_rd_off(D0, 0, 0)>(vb), h0 = tr_read<v_rd_off(D0, 0, 1)>(vb), l1 = tr_read<v_rd_off(D0, 1, 0)>(vb), h1 = tr_read<v_rd_off(D0, 1, 1)>(vb);
;   const s16x4 l2 = tr_read<v_rd_off(D0, 2, 0)>(vb), h2 = tr_read<v_rd_off(D0, 2, 1)>(vb), l3 = tr_read<v_rd_off(D0, 3, 0)>(vb), h3 = tr_read<v_rd_off(D0, 3, 1)>(vb);
;   asm volatile("s_waitcnt lgkmcnt(0)" ::: "memory"); SBAR();
;     ...
;   od = __builtin_amdgcn_mfma_f32_32x32x16_bf16(pa0, PK(l0, h0), od, 0, 0, 0);
;   od = __builtin_amdgcn_mfma_f32_32x32x16_bf16(pa1, PK(l1, h1), od, 0, 0, 0);
;   od = __builtin_amdgcn_mfma_f32_32x32x16_bf16(pa2, PK(l2, h2), od, 0, 0, 0);
;   od = __builtin_amdgcn_mfma_f32_32x32x16_bf16(pa3, PK(l3, h3), od, 0, 0, 0);
;     ...
; }
; __device__ __forceinline__ void pv_d0(f32x16* o, int vb, bf16x8 pa0, bf16x8 pa1, bf16x8 pa2, bf16x8 pa3) {
;   pv_one<0>(o[0], vb, pa0, pa1, pa2, pa3); pv_one<1>(o[1], vb, pa0, pa1, pa2, pa3); pv_one<2>(o[2], vb, pa0, pa1, pa2, pa3); pv_one<3>(o[3], vb, pa0, pa1, pa2, pa3);
.Ldw_skipA1:
	v_lshl_add_u32 v218, s9, 14, v181
	ds_read_b64_tr_b16 v[202:203], v218 offset:0
	ds_read_b64_tr_b16 v[204:205], v218 offset:0x800
	ds_read_b64_tr_b16 v[206:207], v218 offset:0x1000
	ds_read_b64_tr_b16 v[208:209], v218 offset:0x1800
	ds_read_b64_tr_b16 v[210:211], v218 offset:0x2000
	ds_read_b64_tr_b16 v[212:213], v218 offset:0x2800
	ds_read_b64_tr_b16 v[214:215], v218 offset:0x3000
	ds_read_b64_tr_b16 v[216:217], v218 offset:0x3800
	s_waitcnt lgkmcnt(6)
	s_nop 0
	v_mfma_f32_32x32x16_bf16 v[2:17], v[82:85], v[202:205], v[2:17]
	ds_read_b64_tr_b16 v[202:203], v218 offset:0x200
	ds_read_b64_tr_b16 v[204:205], v218 offset:0xa00
	s_waitcnt lgkmcnt(6)
	v_mfma_f32_32x32x16_bf16 v[2:17], v[86:89], v[206:209], v[2:17]
	ds_read_b64_tr_b16 v[206:207], v218 offset:0x1200
	ds_read_b64_tr_b16 v[208:209], v218 offset:0x1a00
	s_waitcnt lgkmcnt(6)
	v_mfma_f32_32x32x16_bf16 v[2:17], v[90:93], v[210:213], v[2:17]
	ds_read_b64_tr_b16 v[210:211], v218 offset:0x2200
	ds_read_b64_tr_b16 v[212:213], v218 offset:0x2a00
	s_waitcnt lgkmcnt(6)
	v_mfma_f32_32x32x16_bf16 v[2:17], v[94:97], v[214:217], v[2:17]
	ds_read_b64_tr_b16 v[214:215], v218 offset:0x3200
	ds_read_b64_tr_b16 v[216:217], v218 offset:0x3a00
	s_waitcnt lgkmcnt(6)
	v_mfma_f32_32x32x16_bf16 v[50:65], v[82:85], v[202:205], v[50:65]
	ds_read_b64_tr_b16 v[202:203], v218 offset:0x400
	ds_read_b64_tr_b16 v[204:205], v218 offset:0xc00
	s_waitcnt lgkmcnt(6)
	v_mfma_f32_32x32x16_bf16 v[50:65], v[86:89], v[206:209], v[50:65]
	ds_read_b64_tr_b16 v[206:207], v218 offset:0x1400
	ds_read_b64_tr_b16 v[208:209], v218 offset:0x1c00
	s_waitcnt lgkmcnt(6)
	v_mfma_f32_32x32x16_bf16 v[50:65], v[90:93], v[210:213], v[50:65]
	ds_read_b64_tr_b16 v[210:211], v218 offset:0x2400
	ds_read_b64_tr_b16 v[212:213], v218 offset:0x2c00
	s_waitcnt lgkmcnt(6)
	v_mfma_f32_32x32x16_bf16 v[50:65], v[94:97], v[214:217], v[50:65]
	ds_read_b64_tr_b16 v[214:215], v218 offset:0x3400
	ds_read_b64_tr_b16 v[216:217], v218 offset:0x3c00
	s_waitcnt lgkmcnt(6)
	v_mfma_f32_32x32x16_bf16 v[34:49], v[82:85], v[202:205], v[34:49]
	ds_read_b64_tr_b16 v[202:203], v218 offset:0x600
	ds_read_b64_tr_b16 v[204:205], v218 offset:0xe00
	s_waitcnt lgkmcnt(6)
	v_mfma_f32_32x32x16_bf16 v[34:49], v[86:89], v[206:209], v[34:49]
	ds_read_b64_tr_b16 v[206:207], v218 offset:0x1600
	ds_read_b64_tr_b16 v[208:209], v218 offset:0x1e00
	s_waitcnt lgkmcnt(6)
	v_mfma_f32_32x32x16_bf16 v[34:49], v[90:93], v[210:213], v[34:49]
	ds_read_b64_tr_b16 v[210:211], v218 offset:0x2600
	ds_read_b64_tr_b16 v[212:213], v218 offset:0x2e00
	s_waitcnt lgkmcnt(6)
	v_mfma_f32_32x32x16_bf16 v[34:49], v[94:97], v[214:217], v[34:49]
	ds_read_b64_tr_b16 v[214:215], v218 offset:0x3600
	ds_read_b64_tr_b16 v[216:217], v218 offset:0x3e00
	s_waitcnt lgkmcnt(6)
	v_mfma_f32_32x32x16_bf16 v[18:33], v[82:85], v[202:205], v[18:33]
	v_max_f32_e32 v82, v115, v115
	v_max_f32_e32 v83, v114, v114
	v_max_f32_e32 v82, v83, v82
	v_max3_f32 v82, v82, v116, v117
	v_max3_f32 v82, v82, v118, v119
	v_max3_f32 v82, v82, v120, v121
	v_max3_f32 v82, v82, v122, v123
	s_waitcnt lgkmcnt(4)
	v_mfma_f32_32x32x16_bf16 v[18:33], v[86:89], v[206:209], v[18:33]
	v_max3_f32 v82, v82, v124, v125
	v_max3_f32 v82, v82, v126, v127
	v_max3_f32 v82, v82, v128, v129
	v_max3_f32 v82, v82, v98, v99
	v_max3_f32 v82, v82, v100, v101
	v_max3_f32 v82, v82, v102, v103
	v_max3_f32 v82, v82, v104, v105
	s_waitcnt lgkmcnt(2)
	v_mfma_f32_32x32x16_bf16 v[18:33], v[90:93], v[210:213], v[18:33]
	v_max3_f32 v82, v82, v106, v107
	v_max3_f32 v82, v82, v108, v109
	v_max3_f32 v82, v82, v110, v111
	v_max3_f32 v82, v82, v112, v113
	v_mov_b32_e32 v83, v82
	s_nop 1
	v_permlane32_swap_b32_e32 v82, v83
	s_waitcnt lgkmcnt(0)
	v_mfma_f32_32x32x16_bf16 v[18:33], v[94:97], v[214:217], v[18:33]
	v_max_f32_e32 v83, v83, v83
	v_max_f32_e32 v82, v82, v82
	v_max_f32_e32 v82, v82, v83
	v_readlane_b32 s18, v255, 8
	s_nop 3
	s_cmp_lt_u32 s18, 4
	s_cbranch_scc1 .Ldw_skipB1
	s_lshl_b32 s13, s12, 14
	s_add_i32 s11, s13, 0
	v_add_u32_e32 v202, s11, v192
	s_waitcnt vmcnt(0)
	s_waitcnt vmcnt(3)
	ds_write_b128 v202, v[146:149]
	v_add_u32_e32 v146, s11, v193
	s_waitcnt vmcnt(1)
	ds_write_b128 v146, v[150:153]
	v_add_u32_e32 v146, s11, v194
	s_mov_b32 s8, 0xfffa0000
	s_waitcnt vmcnt(1)
	ds_write_b128 v146, v[154:157] offset:49152
	s_waitcnt vmcnt(0)
	ds_write_b128 v146, v[158:161] offset:57344
	v_add_co_u32_e32 v146, vcc, s8, v166
	s_mov_b32 s8, 0xfffc0000
	s_nop 0
	v_addc_co_u32_e32 v147, vcc, -1, v167, vcc
	v_add_co_u32_e32 v150, vcc, s8, v166
	s_mov_b32 s8, 0xfb7a0000
	s_nop 0
	v_addc_co_u32_e32 v151, vcc, -1, v167, vcc
	v_add_co_u32_e32 v154, vcc, s8, v166
	s_mov_b32 s8, 0xfb7c0000
	s_nop 0
	v_addc_co_u32_e32 v155, vcc, -1, v167, vcc
	v_add_co_u32_e32 v158, vcc, s8, v166
	global_load_dwordx4 v[146:149], v[146:147], off
	s_nop 0
	global_load_dwordx4 v[150:153], v[150:151], off
	v_addc_co_u32_e32 v159, vcc, -1, v167, vcc
	global_load_dwordx4 v[154:157], v[154:155], off
	s_nop 0
	global_load_dwordx4 v[158:161], v[158:159], off
.Ldw_skipB1:
	v_cmp_ge_f32_e32 vcc, s0, v82
	s_cmp_eq_u64 vcc, exec
	s_cbranch_scc0 .LBB0_331
	v_mov_b32_e32 v203, 1.0

; template <bool FIRST> __device__ __forceinline__ void partialSM_ps(f32x16& p0, f32x16& p1, float& m_reg, float& alpha, f32x16& negm) {
;     ...
; #pragma unroll
;   for (int r = 0; r < 16; ++r) p0[r] = __builtin_amdgcn_exp2f(p0[r]);
; }
; __device__ __forceinline__ void finishSM(f32x16& p0, f32x16& p1, float alpha, float& l_reg, bf16x8& pa0, bf16x8& pa1, bf16x8& pa2, bf16x8& pa3) {
; #pragma unroll
;   for (int r = 0; r < 16; ++r) p1[r] = __builtin_amdgcn_exp2f(p1[r]);
;   float ps = 0;
; #pragma unroll
;   for (int r = 0; r < 16; ++r) ps += p0[r];
; #pragma unroll
;   for (int r = 0; r < 16; ++r) ps += p1[r];
;   { auto rr = __builtin_amdgcn_permlane32_swap(__float_as_uint(ps), __float_as_uint(ps), false, false);
;     ps = __uint_as_float(rr[0]) + __uint_as_float(rr[1]); }
;   l_reg = l_reg * alpha + ps;
;     ...
;   PK4(p0, 0, pa0); PK4(p0, 8, pa1); PK4(p1, 0, pa2); PK4(p1, 8, pa3);
;     ...
; }
; template <int DQK, int KW, int QSP> __device__ __forceinline__ void qkt(f32x16& p0, f32x16& p1, const char* Ks, const int (&kb)[4], const bf16x8* qr, const char* qsp, const f32x16& cinit) {
;   p0 = cinit; p1 = cinit;
;   constexpr int N = DQK / 16;
;     ...
;   bf16x8 f0[2], f1[2];
;   f0[0] = KRD(0, 1); f1[0] = KRD(0, 0);
; #pragma unroll
;   for (int d0 = 0; d0 < N; ++d0) {
;     if (d0 + 1 < N) { f0[(d0 + 1) & 1] = KRD(d0 + 1, 1); f1[(d0 + 1) & 1] = KRD(d0 + 1, 0); }
;     __builtin_amdgcn_sched_barrier(0x406);
;     bf16x8 qf;
;     if constexpr (QSP > 0) { if (d0 >= N - QSP) qf = *reinterpret_cast<const bf16x8*>(qsp + (d0 - (N - QSP)) * 1024); else qf = qr[d0]; } else qf = qr[d0];
;     p0 = __builtin_amdgcn_mfma_f32_32x32x16_bf16(f0[d0 & 1], qf, p0, 0, 0, 0);
;     p1 = __builtin_amdgcn_mfma_f32_32x32x16_bf16(f1[d0 & 1], qf, p1, 0, 0, 0);
;     __builtin_amdgcn_sched_barrier(0x406); }
; template <int DQK, int KW, bool DIFF, int SDEPTH, int QSP, int NBUF>
; __device__ __forceinline__ void attn_unit(const UnitP& P, char* lds) {
;     ...
;   f32x16 pA0, pA1, pB0, pB1; float mnA, mnB, alA, alB; bf16x8 pa0, pa1, pa2, pa3; const int NT = P.nt;
;   if constexpr (NBUF == 3) {
.LBB0_322:
	s_add_i32 s8, s12, 1
	s_cmp_lg_u32 s12, 2
	s_cselect_b32 s35, s8, 0
	v_exp_f32_e32 v202, v114
	v_exp_f32_e32 v220, v115
	v_exp_f32_e32 v221, v116
	v_exp_f32_e32 v222, v117
	v_exp_f32_e32 v223, v118
	v_exp_f32_e32 v224, v119
	v_exp_f32_e32 v225, v120
	v_exp_f32_e32 v226, v121
	v_exp_f32_e32 v227, v122
	v_exp_f32_e32 v228, v123
	v_exp_f32_e32 v229, v124
	v_exp_f32_e32 v230, v125
	v_exp_f32_e32 v231, v126
	v_exp_f32_e32 v232, v127
	v_exp_f32_e32 v233, v128
	v_exp_f32_e32 v234, v129
	v_add_u32_e32 v86, s11, v183
	ds_read_b128 v[82:85], v86 offset:49152
	v_add_u32_e32 v87, s11, v197
	ds_read_b128 v[204:207], v86 offset:57344
	ds_read_b128 v[208:211], v87 offset:49152
	ds_read_b128 v[212:215], v87 offset:57344
	v_add_u32_e32 v216, s11, v196
	v_exp_f32_e32 v235, v112
	v_exp_f32_e32 v113, v113
	s_waitcnt lgkmcnt(3)
	v_mfma_f32_32x32x16_bf16 v[114:129], v[82:85], v[142:145], v[66:81]
	s_waitcnt lgkmcnt(2)
	v_mfma_f32_32x32x16_bf16 v[82:97], v[204:207], v[142:145], v[66:81]
	ds_read_b128 v[204:207], v216 offset:49152
	ds_read_b128 v[216:219], v216 offset:57344
	s_waitcnt lgkmcnt(3)
	v_mfma_f32_32x32x16_bf16 v[114:129], v[208:211], v[138:141], v[114:129]
	s_waitcnt lgkmcnt(2)
	v_mfma_f32_32x32x16_bf16 v[82:97], v[212:215], v[138:141], v[82:97]
	v_add_u32_e32 v212, s11, v198
	ds_read_b128 v[208:211], v212 offset:49152
	ds_read_b128 v[212:215], v212 offset:57344
	s_waitcnt lgkmcnt(3)
	v_mfma_f32_32x32x16_bf16 v[114:129], v[204:207], v[134:137], v[114:129]
	v_exp_f32_e32 v206, v98
	v_add_f32_e32 v98, 0, v202
	v_add_f32_e32 v98, v220, v98
	v_add_f32_e32 v98, v221, v98
	v_add_f32_e32 v98, v222, v98
	v_add_f32_e32 v98, v223, v98
	v_add_f32_e32 v98, v224, v98
	v_add_f32_e32 v98, v225, v98
	v_add_f32_e32 v98, v226, v98
	v_add_f32_e32 v98, v227, v98
	v_add_f32_e32 v98, v228, v98
	s_waitcnt lgkmcnt(2)
	v_mfma_f32_32x32x16_bf16 v[82:97], v[216:219], v[134:137], v[82:97]
	v_add_f32_e32 v98, v229, v98
	v_add_f32_e32 v98, v230, v98
	v_add_f32_e32 v98, v231, v98
	v_exp_f32_e32 v207, v99
	v_add_f32_e32 v98, v232, v98
	v_add_f32_e32 v98, v233, v98
	v_add_f32_e32 v98, v234, v98
	s_waitcnt lgkmcnt(1)
	v_mfma_f32_32x32x16_bf16 v[114:129], v[208:211], v[130:133], v[114:129]
	v_exp_f32_e32 v208, v100
	v_exp_f32_e32 v209, v101
	v_exp_f32_e32 v210, v102
	v_add_f32_e32 v98, v206, v98
	v_exp_f32_e32 v211, v103
	v_add_f32_e32 v98, v207, v98
	v_add_f32_e32 v98, v208, v98
	s_waitcnt lgkmcnt(0)
	v_mfma_f32_32x32x16_bf16 v[82:97], v[212:215], v[130:133], v[82:97]
	v_exp_f32_e32 v212, v104
	v_exp_f32_e32 v213, v105
	v_add_f32_e32 v98, v209, v98
	v_exp_f32_e32 v214, v106
	v_add_f32_e32 v98, v210, v98
	v_exp_f32_e32 v215, v107
	v_add_f32_e32 v98, v211, v98
	v_exp_f32_e32 v216, v108
	v_add_f32_e32 v98, v212, v98
	v_exp_f32_e32 v217, v109
	v_add_f32_e32 v98, v213, v98
	v_exp_f32_e32 v218, v110
	v_add_f32_e32 v98, v214, v98
	v_exp_f32_e32 v219, v111
	v_add_f32_e32 v98, v215, v98
	v_add_f32_e32 v98, v216, v98
	v_add_f32_e32 v98, v217, v98
	v_add_f32_e32 v98, v218, v98
	v_add_f32_e32 v98, v219, v98
	v_add_f32_e32 v98, v235, v98
	v_add_f32_e32 v204, v113, v98
	v_mov_b32_e32 v205, v204
	v_cvt_pk_bf16_f32 v98, v202, v220
	v_cvt_pk_bf16_f32 v99, v221, v222
	v_cvt_pk_bf16_f32 v100, v223, v224
	v_cvt_pk_bf16_f32 v101, v225, v226
	v_cvt_pk_bf16_f32 v102, v227, v228
	v_cvt_pk_bf16_f32 v103, v229, v230
	v_cvt_pk_bf16_f32 v104, v231, v232
	v_cvt_pk_bf16_f32 v105, v233, v234
	v_cvt_pk_bf16_f32 v106, v206, v207
	v_cvt_pk_bf16_f32 v107, v208, v209
	v_cvt_pk_bf16_f32 v108, v210, v211
	v_cvt_pk_bf16_f32 v109, v212, v213
	v_cvt_pk_bf16_f32 v110, v214, v215
	v_cvt_pk_bf16_f32 v111, v216, v217
	v_cvt_pk_bf16_f32 v112, v218, v219
	v_cvt_pk_bf16_f32 v113, v235, v113
	s_nop 1
	v_permlane32_swap_b32_e32 v204, v205
	v_permlane32_swap_b32_e32 v98, v100
	v_permlane32_swap_b32_e32 v99, v101
	v_permlane32_swap_b32_e32 v102, v104
	v_permlane32_swap_b32_e32 v103, v105
	v_permlane32_swap_b32_e32 v106, v108
	v_permlane32_swap_b32_e32 v107, v109
	v_permlane32_swap_b32_e32 v110, v112
	v_permlane32_swap_b32_e32 v111, v113
	v_readlane_b32 s18, v255, 8
	s_nop 3
	s_cmp_ge_u32 s18, 4
	s_cbranch_scc1 .LBB0_324
	s_lshl_b32 s33, s35, 14
	s_add_i32 s36, s33, 0
	s_waitcnt vmcnt(0)
	v_add_u32_e32 v202, s36, v192
	s_cmp_ge_u32 s30, s31
	s_waitcnt vmcnt(3)
	ds_write_b128 v202, v[146:149]
	v_add_u32_e32 v202, s36, v193
	s_cselect_b64 s[8:9], -1, 0
	s_waitcnt vmcnt(2)
	ds_write_b128 v202, v[150:153]
	v_add_u32_e32 v202, s33, v195
	s_and_b64 vcc, exec, s[8:9]
	s_waitcnt vmcnt(1)
	ds_write_b128 v202, v[154:157] offset:49152
	s_waitcnt vmcnt(0)
	ds_write_b128 v202, v[158:161] offset:57344
	s_cbranch_vccnz .LBB0_324
	v_add_co_u32_e32 v146, vcc, 0xfffe0000, v166
	s_nop 1
	v_addc_co_u32_e32 v147, vcc, -1, v167, vcc
	v_add_co_u32_e32 v150, vcc, 0xfb7e0000, v166
	s_nop 1
	v_addc_co_u32_e32 v151, vcc, -1, v167, vcc
	v_add_co_u32_e32 v158, vcc, 0xfb800000, v166
	global_load_dwordx4 v[146:149], v[146:147], off
	s_nop 0
	global_load_dwordx4 v[154:157], v[150:151], off
	v_addc_co_u32_e32 v159, vcc, -1, v167, vcc
	global_load_dwordx4 v[150:153], v[166:167], off
	s_nop 0
	global_load_dwordx4 v[158:161], v[158:159], off
; #define SBAR() __builtin_amdgcn_sched_barrier(0)
; template <bool FIRST> __device__ __forceinline__ void partialSM_ps(f32x16& p0, f32x16& p1, float& m_reg, float& alpha, f32x16& negm) {
;   float pmax = p0[0];
; #pragma unroll
;   for (int r = 1; r < 16; ++r) pmax = fmaxf(pmax, p0[r]);
; #pragma unroll
;   for (int r = 0; r < 16; ++r) pmax = fmaxf(pmax, p1[r]);
;   { auto rr = __builtin_amdgcn_permlane32_swap(__float_as_uint(pmax), __float_as_uint(pmax), false, false);
;     pmax = fmaxf(__uint_as_float(rr[0]), __uint_as_float(rr[1])); }
;   alpha = 1.f;
;   if (FIRST || !__builtin_expect(__all(pmax <= THRL), 1)) {
; template <int OFF> __device__ __forceinline__ s16x4 tr_read(int vb) {
;   s16x4 r; asm volatile("ds_read_b64_tr_b16 %0, %1 offset:%2" : "=&v"(r) : "v"(vb), "i"(OFF) : "memory"); return r;
; }
; template <int D0> __device__ __forceinline__ void pv_one(f32x16& od, int vb, bf16x8 pa0, bf16x8 pa1, bf16x8 pa2, bf16x8 pa3) {
;   const s16x4 l0 = tr_read<v_rd_off(D0, 0, 0)>(vb), h0 = tr_read<v_rd_off(D0, 0, 1)>(vb), l1 = tr_read<v_rd_off(D0, 1, 0)>(vb), h1 = tr_read<v_rd_off(D0, 1, 1)>(vb);
;   const s16x4 l2 = tr_read<v_rd_off(D0, 2, 0)>(vb), h2 = tr_read<v_rd_off(D0, 2, 1)>(vb), l3 = tr_read<v_rd_off(D0, 3, 0)>(vb), h3 = tr_read<v_rd_off(D0, 3, 1)>(vb);
;   asm volatile("s_waitcnt lgkmcnt(0)" ::: "memory"); SBAR();
;     ...
;   od = __builtin_amdgcn_mfma_f32_32x32x16_bf16(pa0, PK(l0, h0), od, 0, 0, 0);
;   od = __builtin_amdgcn_mfma_f32_32x32x16_bf16(pa1, PK(l1, h1), od, 0, 0, 0);
;   od = __builtin_amdgcn_mfma_f32_32x32x16_bf16(pa2, PK(l2, h2), od, 0, 0, 0);
;   od = __builtin_amdgcn_mfma_f32_32x32x16_bf16(pa3, PK(l3, h3), od, 0, 0, 0);
;     ...
; }
; __device__ __forceinline__ void pv_d0(f32x16* o, int vb, bf16x8 pa0, bf16x8 pa1, bf16x8 pa2, bf16x8 pa3) {
;   pv_one<0>(o[0], vb, pa0, pa1, pa2, pa3); pv_one<1>(o[1], vb, pa0, pa1, pa2, pa3); pv_one<2>(o[2], vb, pa0, pa1, pa2, pa3); pv_one<3>(o[3], vb, pa0, pa1, pa2, pa3);
; template <int DQK, int KW, bool DIFF, int SDEPTH, int QSP, int NBUF>
; __device__ __forceinline__ void attn_unit(const UnitP& P, char* lds) {
;     ...
;   f32x16 pA0, pA1, pB0, pB1; float mnA, mnB, alA, alB; bf16x8 pa0, pa1, pa2, pa3; const int NT = P.nt;
;   if constexpr (NBUF == 3) {
.LBB0_324:
	v_add_u32_e32 v202, s10, v181
	ds_read_b64_tr_b16 v[206:207], v202 offset:0
	ds_read_b64_tr_b16 v[208:209], v202 offset:0x800
	ds_read_b64_tr_b16 v[210:211], v202 offset:0x1000
	ds_read_b64_tr_b16 v[212:213], v202 offset:0x1800
	ds_read_b64_tr_b16 v[214:215], v202 offset:0x2000
	ds_read_b64_tr_b16 v[216:217], v202 offset:0x2800
	ds_read_b64_tr_b16 v[218:219], v202 offset:0x3000
	ds_read_b64_tr_b16 v[220:221], v202 offset:0x3800
	s_waitcnt lgkmcnt(6)
	s_nop 0
	v_mfma_f32_32x32x16_bf16 v[2:17], v[98:101], v[206:209], v[2:17]
	ds_read_b64_tr_b16 v[206:207], v202 offset:0x200
	ds_read_b64_tr_b16 v[208:209], v202 offset:0xa00
	s_waitcnt lgkmcnt(6)
	v_mfma_f32_32x32x16_bf16 v[2:17], v[102:105], v[210:213], v[2:17]
	ds_read_b64_tr_b16 v[210:211], v202 offset:0x1200
	ds_read_b64_tr_b16 v[212:213], v202 offset:0x1a00
	s_waitcnt lgkmcnt(6)
	v_mfma_f32_32x32x16_bf16 v[2:17], v[106:109], v[214:217], v[2:17]
	ds_read_b64_tr_b16 v[214:215], v202 offset:0x2200
	ds_read_b64_tr_b16 v[216:217], v202 offset:0x2a00
	s_waitcnt lgkmcnt(6)
	v_mfma_f32_32x32x16_bf16 v[2:17], v[110:113], v[218:221], v[2:17]
	ds_read_b64_tr_b16 v[218:219], v202 offset:0x3200
	ds_read_b64_tr_b16 v[220:221], v202 offset:0x3a00
	s_waitcnt lgkmcnt(6)
	v_mfma_f32_32x32x16_bf16 v[50:65], v[98:101], v[206:209], v[50:65]
	ds_read_b64_tr_b16 v[206:207], v202 offset:0x400
	ds_read_b64_tr_b16 v[208:209], v202 offset:0xc00
	s_waitcnt lgkmcnt(6)
	v_mfma_f32_32x32x16_bf16 v[50:65], v[102:105], v[210:213], v[50:65]
	ds_read_b64_tr_b16 v[210:211], v202 offset:0x1400
	ds_read_b64_tr_b16 v[212:213], v202 offset:0x1c00
	s_waitcnt lgkmcnt(6)
	v_mfma_f32_32x32x16_bf16 v[50:65], v[106:109], v[214:217], v[50:65]
	ds_read_b64_tr_b16 v[214:215], v202 offset:0x2400
	ds_read_b64_tr_b16 v[216:217], v202 offset:0x2c00
	s_waitcnt lgkmcnt(6)
	v_mfma_f32_32x32x16_bf16 v[50:65], v[110:113], v[218:221], v[50:65]
	ds_read_b64_tr_b16 v[218:219], v202 offset:0x3400
	ds_read_b64_tr_b16 v[220:221], v202 offset:0x3c00
	s_waitcnt lgkmcnt(6)
	v_mfma_f32_32x32x16_bf16 v[34:49], v[98:101], v[206:209], v[34:49]
	ds_read_b64_tr_b16 v[206:207], v202 offset:0x600
	ds_read_b64_tr_b16 v[208:209], v202 offset:0xe00
	s_waitcnt lgkmcnt(6)
	v_mfma_f32_32x32x16_bf16 v[34:49], v[102:105], v[210:213], v[34:49]
	ds_read_b64_tr_b16 v[210:211], v202 offset:0x1600
	ds_read_b64_tr_b16 v[212:213], v202 offset:0x1e00
	s_waitcnt lgkmcnt(6)
	v_mfma_f32_32x32x16_bf16 v[34:49], v[106:109], v[214:217], v[34:49]
	ds_read_b64_tr_b16 v[214:215], v202 offset:0x2600
	ds_read_b64_tr_b16 v[216:217], v202 offset:0x2e00
	s_waitcnt lgkmcnt(6)
	v_mfma_f32_32x32x16_bf16 v[34:49], v[110:113], v[218:221], v[34:49]
	ds_read_b64_tr_b16 v[218:219], v202 offset:0x3600
	ds_read_b64_tr_b16 v[220:221], v202 offset:0x3e00
	s_waitcnt lgkmcnt(6)
	v_mfma_f32_32x32x16_bf16 v[18:33], v[98:101], v[206:209], v[18:33]
	v_max_f32_e32 v98, v115, v115
	v_max_f32_e32 v99, v114, v114
	v_max_f32_e32 v98, v99, v98
	v_max3_f32 v98, v98, v116, v117
	v_max3_f32 v98, v98, v118, v119
	v_max3_f32 v98, v98, v120, v121
	v_max3_f32 v98, v98, v122, v123
	s_waitcnt lgkmcnt(4)
	v_mfma_f32_32x32x16_bf16 v[18:33], v[102:105], v[210:213], v[18:33]
	v_max3_f32 v98, v98, v124, v125
	v_max3_f32 v98, v98, v126, v127
	v_max3_f32 v98, v98, v128, v129
	v_max3_f32 v98, v98, v82, v83
	v_max3_f32 v98, v98, v84, v85
	v_max3_f32 v98, v98, v86, v87
	v_max3_f32 v98, v98, v88, v89
	s_waitcnt lgkmcnt(2)
	v_mfma_f32_32x32x16_bf16 v[18:33], v[106:109], v[214:217], v[18:33]
	v_max3_f32 v98, v98, v90, v91
	v_max3_f32 v98, v98, v92, v93
	v_max3_f32 v98, v98, v94, v95
	v_max3_f32 v98, v98, v96, v97
	v_mov_b32_e32 v99, v98
	s_nop 1
	v_permlane32_swap_b32_e32 v98, v99
	s_waitcnt lgkmcnt(0)
	v_mfma_f32_32x32x16_bf16 v[18:33], v[110:113], v[218:221], v[18:33]
	v_max_f32_e32 v99, v99, v99
	v_max_f32_e32 v98, v98, v98
	v_max_f32_e32 v98, v98, v99
	v_readlane_b32 s18, v255, 8
	s_nop 3
	s_cmp_lt_u32 s18, 4
	s_cbranch_scc1 .Ldw_skipB2
	s_lshl_b32 s33, s35, 14
	s_add_i32 s36, s33, 0
	s_waitcnt vmcnt(0)
	v_add_u32_e32 v202, s36, v192
	s_cmp_ge_u32 s30, s31
	s_waitcnt vmcnt(3)
	ds_write_b128 v202, v[146:149]
	v_add_u32_e32 v202, s36, v193
	s_cselect_b64 s[8:9], -1, 0
	s_waitcnt vmcnt(2)
	ds_write_b128 v202, v[150:153]
	v_add_u32_e32 v202, s33, v195
	s_and_b64 vcc, exec, s[8:9]
	s_waitcnt vmcnt(1)
	ds_write_b128 v202, v[154:157] offset:49152
	s_waitcnt vmcnt(0)
	ds_write_b128 v202, v[158:161] offset:57344
	s_cbranch_vccnz .Ldw_skipB2
	v_add_co_u32_e32 v146, vcc, 0xfffe0000, v166
	s_nop 1
	v_addc_co_u32_e32 v147, vcc, -1, v167, vcc
	v_add_co_u32_e32 v150, vcc, 0xfb7e0000, v166
	s_nop 1
	v_addc_co_u32_e32 v151, vcc, -1, v167, vcc
	v_add_co_u32_e32 v158, vcc, 0xfb800000, v166
	global_load_dwordx4 v[146:149], v[146:147], off
	s_nop 0
	global_load_dwordx4 v[154:157], v[150:151], off
	v_addc_co_u32_e32 v159, vcc, -1, v167, vcc
	global_load_dwordx4 v[150:153], v[166:167], off
	s_nop 0
	global_load_dwordx4 v[158:161], v[158:159], off
.Ldw_skipB2:
	v_cmp_ge_f32_e32 vcc, s0, v98
	s_cmp_eq_u64 vcc, exec
	v_mov_b32_e32 v202, 1.0
	s_cbranch_scc0 .LBB0_332
